# attention FIXED inner loop hand-scheduled: 6-step unroll, prefetched LDS reads, in-place exp
# speedup vs baseline: 1.0573x; 1.0573x over previous
; #define ATT_LOAD(t) do { sk0 = *(const u32x4*)(kp0 + (size_t)(t) * 64 * 768); if (has1) sk1 = *(const u32x4*)(kp1 + (size_t)(t) * 64 * 768); sv = *(const u32x4*)(vp + (t) * 64); } while (0)
; #define ATT_STORE(boff) do { *(LAS u32x4*)(lds + (boff) + kw0) = sk0; if (has1) *(LAS u32x4*)(lds + (boff) + kw1) = sk1; *(LAS u32x4*)(lds + (boff) + vw) = sv; } while (0)
; template <bool FIXED> __device__ __forceinline__ void attn_unit(unsigned char* ws, LAS unsigned char* lds, int b, int h, int qb, const int tid, const float sbound) {
;     ...
;     ATT_LOAD(0); ATT_STORE(0); ATT_LOAD(1); ATT_STORE(ABUF); ATT_LOAD(2);
;     __syncthreads();
;     const int pi_r = (r32 & ~12) | ((r32 & 4) << 1) | ((r32 & 8) >> 1);
;     const int kro = pi_r * AKP + hi * 16, vro = AKB + r32 * AVP + hi * 16;
;     f32x16 o0 = {}, o1 = {}, negm = {};
;     float mref = 0.f, lsum = 0.f;
;     ...
;     if constexpr (FIXED) { for (int kt = 0; kt < SEQ / 64; kt += 2) { ATT_STEP_FIXED(pA0, pA1, pB0, pB1, kt); ATT_STEP_FIXED(pB0, pB1, pA0, pA1, kt + 1); }
.LBB0_758:
	s_add_u32 s6, s74, s47
	s_addc_u32 s7, s75, s46
	s_add_u32 s6, s6, s88
	s_addc_u32 s7, s7, 0
	s_add_u32 s6, s6, 0x1a048000
	s_addc_u32 s7, s7, 0
	s_add_i32 s40, s50, s17
	s_lshl_b32 s40, s40, 20
	s_add_u32 s40, s40, s74
	s_addc_u32 s41, s75, 0
	s_add_u32 s40, s40, 0x18000180
	s_addc_u32 s41, s41, 0
	s_mov_b32 s14, 0
	ds_read_b128 v[128:131], v209 offset:13312
	ds_read_b128 v[132:135], v209 offset:17920
	ds_read_b128 v[136:139], v209 offset:13344
	ds_read_b128 v[140:143], v209 offset:17952
	s_nop 7
	s_nop 7
	v_exp_f32_e32 v64, v64
	v_exp_f32_e32 v65, v65
	v_exp_f32_e32 v66, v66
	v_exp_f32_e32 v67, v67
	v_exp_f32_e32 v68, v68
	v_exp_f32_e32 v69, v69
	v_exp_f32_e32 v70, v70
	v_exp_f32_e32 v71, v71
	v_exp_f32_e32 v72, v72
	v_exp_f32_e32 v73, v73
	v_exp_f32_e32 v74, v74
	v_exp_f32_e32 v75, v75
	v_cvt_pk_bf16_f32 v112, v64, v65
	v_cvt_pk_bf16_f32 v113, v66, v67
	v_cvt_pk_bf16_f32 v114, v68, v69
	v_cvt_pk_bf16_f32 v115, v70, v71
	v_exp_f32_e32 v76, v76
	v_exp_f32_e32 v77, v77
	v_exp_f32_e32 v78, v78
	v_exp_f32_e32 v79, v79
	s_nop 0
	v_cvt_pk_bf16_f32 v116, v72, v73
	v_cvt_pk_bf16_f32 v117, v74, v75
	v_cvt_pk_bf16_f32 v118, v76, v77
	v_cvt_pk_bf16_f32 v119, v78, v79
	s_nop 1
.Lattn_fx_loop:
	ds_read_b128 v[188:191], v187 offset:22528
	ds_read_b128 v[168:171], v187 offset:22560
	s_waitcnt lgkmcnt(5)
	v_mfma_f32_32x32x16_bf16 v[16:31], v[128:131], v[112:115], v[16:31]
	ds_read_b128 v[220:223], v187 offset:22592
	s_waitcnt vmcnt(0)
	ds_write_b128 v211, v[176:179] offset:45056
	s_and_saveexec_b64 s[42:43], s[36:37]
	s_cbranch_execz .Lattn_fx_w0
	ds_write_b128 v186, v[172:175] offset:45056
.Lattn_fx_w0:
	s_or_b64 exec, exec, s[42:43]
	ds_write_b128 v208, v[180:183] offset:58368
	v_exp_f32_e32 v48, v48
	v_exp_f32_e32 v49, v49
	v_exp_f32_e32 v50, v50
	v_exp_f32_e32 v51, v51
	s_waitcnt lgkmcnt(7)
	v_mfma_f32_32x32x16_bf16 v[32:47], v[132:135], v[112:115], v[32:47]
	ds_read_b128 v[128:131], v187 offset:22624
	global_load_dwordx4 v[176:179], v212, s[6:7]
	s_and_saveexec_b64 s[42:43], s[36:37]
	s_cbranch_execz .Lattn_fx_g1
	global_load_dwordx4 v[172:175], v214, s[6:7]
.Lattn_fx_g1:
	s_or_b64 exec, exec, s[42:43]
	global_load_dwordx4 v[180:183], v204, s[40:41]
	s_add_u32 s6, s6, 0x18000
	s_addc_u32 s7, s7, 0
	s_add_u32 s40, s40, 0x80
	s_addc_u32 s41, s41, 0
	v_exp_f32_e32 v52, v52
	v_exp_f32_e32 v53, v53
	v_exp_f32_e32 v54, v54
	v_exp_f32_e32 v55, v55
	s_waitcnt lgkmcnt(7)
	v_mfma_f32_32x32x16_bf16 v[16:31], v[136:139], v[116:119], v[16:31]
	ds_read_b128 v[132:135], v187 offset:22656
	v_cvt_pk_bf16_f32 v120, v48, v49
	v_cvt_pk_bf16_f32 v121, v50, v51
	v_cvt_pk_bf16_f32 v122, v52, v53
	v_cvt_pk_bf16_f32 v123, v54, v55
	s_waitcnt lgkmcnt(7)
	v_mfma_f32_32x32x16_bf16 v[32:47], v[140:143], v[116:119], v[32:47]
	ds_read_b128 v[136:139], v187 offset:22688
	v_exp_f32_e32 v56, v56
	v_exp_f32_e32 v57, v57
	v_exp_f32_e32 v58, v58
	v_exp_f32_e32 v59, v59
	s_waitcnt lgkmcnt(7)
	v_mfma_f32_32x32x16_bf16 v[96:111], v[188:191], v[164:167], v[0:15]
	ds_read_b128 v[140:143], v209 offset:13376
	v_exp_f32_e32 v60, v60
	v_exp_f32_e32 v61, v61
	v_exp_f32_e32 v62, v62
	v_exp_f32_e32 v63, v63
	s_waitcnt lgkmcnt(7)
	v_mfma_f32_32x32x16_bf16 v[96:111], v[168:171], v[144:147], v[96:111]
	ds_read_b128 v[188:191], v209 offset:17984
	v_cvt_pk_bf16_f32 v124, v56, v57
	v_cvt_pk_bf16_f32 v125, v58, v59
	v_cvt_pk_bf16_f32 v126, v60, v61
	v_cvt_pk_bf16_f32 v127, v62, v63
	s_waitcnt lgkmcnt(7)
	v_mfma_f32_32x32x16_bf16 v[96:111], v[220:223], v[148:151], v[96:111]
	ds_read_b128 v[168:171], v187 offset:29184
	v_add_f32_e32 v48, v64, v48
	v_add_f32_e32 v244, v244, v48
	v_add_f32_e32 v49, v65, v49
	v_add_f32_e32 v245, v245, v49
	s_waitcnt lgkmcnt(5)
	v_mfma_f32_32x32x16_bf16 v[96:111], v[128:131], v[152:155], v[96:111]
	ds_read_b128 v[220:223], v187 offset:29216
	v_add_f32_e32 v50, v66, v50
	v_add_f32_e32 v242, v242, v50
	v_add_f32_e32 v51, v67, v51
	v_add_f32_e32 v243, v243, v51
	s_waitcnt lgkmcnt(5)
	v_mfma_f32_32x32x16_bf16 v[96:111], v[132:135], v[156:159], v[96:111]
	ds_read_b128 v[128:131], v187 offset:29248
	v_add_f32_e32 v52, v68, v52
	v_add_f32_e32 v240, v240, v52
	v_add_f32_e32 v53, v69, v53
	v_add_f32_e32 v241, v241, v53
	s_waitcnt lgkmcnt(5)
	v_mfma_f32_32x32x16_bf16 v[96:111], v[136:139], v[160:163], v[96:111]
	ds_read_b128 v[132:135], v209 offset:13408
	v_add_f32_e32 v54, v70, v54
	v_add_f32_e32 v238, v238, v54
	v_add_f32_e32 v55, v71, v55
	v_add_f32_e32 v239, v239, v55
	s_waitcnt lgkmcnt(5)
	v_mfma_f32_32x32x16_bf16 v[16:31], v[140:143], v[120:123], v[16:31]
	ds_read_b128 v[136:139], v209 offset:18016
	v_add_f32_e32 v56, v72, v56
	v_add_f32_e32 v236, v236, v56
	v_add_f32_e32 v57, v73, v57
	v_add_f32_e32 v237, v237, v57
	s_waitcnt lgkmcnt(5)
	v_mfma_f32_32x32x16_bf16 v[32:47], v[188:191], v[120:123], v[32:47]
	ds_read_b128 v[140:143], v187 offset:29280
	v_add_f32_e32 v58, v74, v58
	v_add_f32_e32 v234, v234, v58
	v_add_f32_e32 v59, v75, v59
	v_add_f32_e32 v235, v235, v59
	s_waitcnt lgkmcnt(5)
	v_mfma_f32_32x32x16_bf16 v[80:95], v[168:171], v[164:167], v[0:15]
	ds_read_b128 v[188:191], v187 offset:29312
	v_exp_f32_e32 v96, v96
	v_exp_f32_e32 v97, v97
	v_exp_f32_e32 v98, v98
	v_exp_f32_e32 v99, v99
	s_waitcnt lgkmcnt(5)
	v_mfma_f32_32x32x16_bf16 v[80:95], v[220:223], v[144:147], v[80:95]
	ds_read_b128 v[168:171], v187 offset:29344
	v_exp_f32_e32 v100, v100
	v_exp_f32_e32 v101, v101
	v_exp_f32_e32 v102, v102
	v_exp_f32_e32 v103, v103
	s_waitcnt lgkmcnt(5)
	v_mfma_f32_32x32x16_bf16 v[80:95], v[128:131], v[148:151], v[80:95]
	ds_read_b128 v[128:131], v209 offset:35840
	v_cvt_pk_bf16_f32 v112, v96, v97
	v_cvt_pk_bf16_f32 v113, v98, v99
	v_cvt_pk_bf16_f32 v114, v100, v101
	v_cvt_pk_bf16_f32 v115, v102, v103
	s_waitcnt lgkmcnt(5)
	v_mfma_f32_32x32x16_bf16 v[16:31], v[132:135], v[124:127], v[16:31]
	ds_read_b128 v[132:135], v209 offset:40448
	v_exp_f32_e32 v104, v104
	v_exp_f32_e32 v105, v105
	v_exp_f32_e32 v106, v106
	v_exp_f32_e32 v107, v107
	s_waitcnt lgkmcnt(5)
	v_mfma_f32_32x32x16_bf16 v[32:47], v[136:139], v[124:127], v[32:47]
	ds_read_b128 v[136:139], v209 offset:35872
	v_exp_f32_e32 v108, v108
	v_exp_f32_e32 v109, v109
	v_exp_f32_e32 v110, v110
	v_exp_f32_e32 v111, v111
	s_waitcnt lgkmcnt(5)
	v_mfma_f32_32x32x16_bf16 v[80:95], v[140:143], v[152:155], v[80:95]
	ds_read_b128 v[140:143], v209 offset:40480
	v_cvt_pk_bf16_f32 v116, v104, v105
	v_cvt_pk_bf16_f32 v117, v106, v107
	v_cvt_pk_bf16_f32 v118, v108, v109
	v_cvt_pk_bf16_f32 v119, v110, v111
	s_waitcnt lgkmcnt(5)
	v_mfma_f32_32x32x16_bf16 v[80:95], v[188:191], v[156:159], v[80:95]
	v_add_f32_e32 v60, v76, v60
	v_add_f32_e32 v232, v232, v60
	v_add_f32_e32 v61, v77, v61
	v_add_f32_e32 v233, v233, v61
	s_waitcnt lgkmcnt(4)
	v_mfma_f32_32x32x16_bf16 v[80:95], v[168:171], v[160:163], v[80:95]
	v_add_f32_e32 v62, v78, v62
	v_add_f32_e32 v230, v230, v62
	v_add_f32_e32 v63, v79, v63
	v_add_f32_e32 v231, v231, v63
	s_waitcnt lgkmcnt(4)
	s_barrier
; #define ATT_LOAD(t) do { sk0 = *(const u32x4*)(kp0 + (size_t)(t) * 64 * 768); if (has1) sk1 = *(const u32x4*)(kp1 + (size_t)(t) * 64 * 768); sv = *(const u32x4*)(vp + (t) * 64); } while (0)
; #define ATT_STORE(boff) do { *(LAS u32x4*)(lds + (boff) + kw0) = sk0; if (has1) *(LAS u32x4*)(lds + (boff) + kw1) = sk1; *(LAS u32x4*)(lds + (boff) + vw) = sv; } while (0)
; template <bool FIXED> __device__ __forceinline__ void attn_unit(unsigned char* ws, LAS unsigned char* lds, int b, int h, int qb, const int tid, const float sbound) {
;     ...
;     ATT_LOAD(0); ATT_STORE(0); ATT_LOAD(1); ATT_STORE(ABUF); ATT_LOAD(2);
;     __syncthreads();
;     const int pi_r = (r32 & ~12) | ((r32 & 4) << 1) | ((r32 & 8) >> 1);
;     const int kro = pi_r * AKP + hi * 16, vro = AKB + r32 * AVP + hi * 16;
;     f32x16 o0 = {}, o1 = {}, negm = {};
;     float mref = 0.f, lsum = 0.f;
;     ...
;     if constexpr (FIXED) { for (int kt = 0; kt < SEQ / 64; kt += 2) { ATT_STEP_FIXED(pA0, pA1, pB0, pB1, kt); ATT_STEP_FIXED(pB0, pB1, pA0, pA1, kt + 1); }
	ds_read_b128 v[188:191], v187 offset:45056
	ds_read_b128 v[168:171], v187 offset:45088
	s_waitcnt lgkmcnt(5)
	v_mfma_f32_32x32x16_bf16 v[16:31], v[128:131], v[112:115], v[16:31]
	ds_read_b128 v[220:223], v187 offset:45120
	s_waitcnt vmcnt(0)
	ds_write_b128 v211, v[176:179] offset:0
	s_and_saveexec_b64 s[42:43], s[36:37]
	s_cbranch_execz .Lattn_fx_w2
	ds_write_b128 v186, v[172:175] offset:0
.Lattn_fx_w2:
	s_or_b64 exec, exec, s[42:43]
	ds_write_b128 v208, v[180:183] offset:13312
	v_exp_f32_e32 v80, v80
	v_exp_f32_e32 v81, v81
	v_exp_f32_e32 v82, v82
	v_exp_f32_e32 v83, v83
	s_waitcnt lgkmcnt(7)
	v_mfma_f32_32x32x16_bf16 v[32:47], v[132:135], v[112:115], v[32:47]
	ds_read_b128 v[128:131], v187 offset:45152
	global_load_dwordx4 v[176:179], v212, s[6:7]
	s_and_saveexec_b64 s[42:43], s[36:37]
	s_cbranch_execz .Lattn_fx_g3
	global_load_dwordx4 v[172:175], v214, s[6:7]
.Lattn_fx_g3:
	s_or_b64 exec, exec, s[42:43]
	global_load_dwordx4 v[180:183], v204, s[40:41]
	s_add_u32 s6, s6, 0x18000
	s_addc_u32 s7, s7, 0
	s_add_u32 s40, s40, 0x80
	s_addc_u32 s41, s41, 0
	v_exp_f32_e32 v84, v84
	v_exp_f32_e32 v85, v85
	v_exp_f32_e32 v86, v86
	v_exp_f32_e32 v87, v87
	s_waitcnt lgkmcnt(7)
	v_mfma_f32_32x32x16_bf16 v[16:31], v[136:139], v[116:119], v[16:31]
	ds_read_b128 v[132:135], v187 offset:45184
	v_cvt_pk_bf16_f32 v120, v80, v81
	v_cvt_pk_bf16_f32 v121, v82, v83
	v_cvt_pk_bf16_f32 v122, v84, v85
	v_cvt_pk_bf16_f32 v123, v86, v87
	s_waitcnt lgkmcnt(7)
	v_mfma_f32_32x32x16_bf16 v[32:47], v[140:143], v[116:119], v[32:47]
	ds_read_b128 v[136:139], v187 offset:45216
	v_exp_f32_e32 v88, v88
	v_exp_f32_e32 v89, v89
	v_exp_f32_e32 v90, v90
	v_exp_f32_e32 v91, v91
	s_waitcnt lgkmcnt(7)
	v_mfma_f32_32x32x16_bf16 v[64:79], v[188:191], v[164:167], v[0:15]
	ds_read_b128 v[140:143], v209 offset:35904
	v_exp_f32_e32 v92, v92
	v_exp_f32_e32 v93, v93
	v_exp_f32_e32 v94, v94
	v_exp_f32_e32 v95, v95
	s_waitcnt lgkmcnt(7)
	v_mfma_f32_32x32x16_bf16 v[64:79], v[168:171], v[144:147], v[64:79]
	ds_read_b128 v[188:191], v209 offset:40512
	v_cvt_pk_bf16_f32 v124, v88, v89
	v_cvt_pk_bf16_f32 v125, v90, v91
	v_cvt_pk_bf16_f32 v126, v92, v93
	v_cvt_pk_bf16_f32 v127, v94, v95
	s_waitcnt lgkmcnt(7)
	v_mfma_f32_32x32x16_bf16 v[64:79], v[220:223], v[148:151], v[64:79]
	ds_read_b128 v[168:171], v187 offset:51712
	v_add_f32_e32 v80, v96, v80
	v_add_f32_e32 v244, v244, v80
	v_add_f32_e32 v81, v97, v81
	v_add_f32_e32 v245, v245, v81
	s_waitcnt lgkmcnt(5)
	v_mfma_f32_32x32x16_bf16 v[64:79], v[128:131], v[152:155], v[64:79]
	ds_read_b128 v[220:223], v187 offset:51744
	v_add_f32_e32 v82, v98, v82
	v_add_f32_e32 v242, v242, v82
	v_add_f32_e32 v83, v99, v83
	v_add_f32_e32 v243, v243, v83
	s_waitcnt lgkmcnt(5)
	v_mfma_f32_32x32x16_bf16 v[64:79], v[132:135], v[156:159], v[64:79]
	ds_read_b128 v[128:131], v187 offset:51776
	v_add_f32_e32 v84, v100, v84
	v_add_f32_e32 v240, v240, v84
	v_add_f32_e32 v85, v101, v85
	v_add_f32_e32 v241, v241, v85
	s_waitcnt lgkmcnt(5)
	v_mfma_f32_32x32x16_bf16 v[64:79], v[136:139], v[160:163], v[64:79]
	ds_read_b128 v[132:135], v209 offset:35936
	v_add_f32_e32 v86, v102, v86
	v_add_f32_e32 v238, v238, v86
	v_add_f32_e32 v87, v103, v87
	v_add_f32_e32 v239, v239, v87
	s_waitcnt lgkmcnt(5)
	v_mfma_f32_32x32x16_bf16 v[16:31], v[140:143], v[120:123], v[16:31]
	ds_read_b128 v[136:139], v209 offset:40544
	v_add_f32_e32 v88, v104, v88
	v_add_f32_e32 v236, v236, v88
	v_add_f32_e32 v89, v105, v89
	v_add_f32_e32 v237, v237, v89
	s_waitcnt lgkmcnt(5)
	v_mfma_f32_32x32x16_bf16 v[32:47], v[188:191], v[120:123], v[32:47]
	ds_read_b128 v[140:143], v187 offset:51808
	v_add_f32_e32 v90, v106, v90
	v_add_f32_e32 v234, v234, v90
	v_add_f32_e32 v91, v107, v91
	v_add_f32_e32 v235, v235, v91
	s_waitcnt lgkmcnt(5)
	v_mfma_f32_32x32x16_bf16 v[48:63], v[168:171], v[164:167], v[0:15]
	ds_read_b128 v[188:191], v187 offset:51840
	v_exp_f32_e32 v64, v64
	v_exp_f32_e32 v65, v65
	v_exp_f32_e32 v66, v66
	v_exp_f32_e32 v67, v67
	s_waitcnt lgkmcnt(5)
	v_mfma_f32_32x32x16_bf16 v[48:63], v[220:223], v[144:147], v[48:63]
	ds_read_b128 v[168:171], v187 offset:51872
	v_exp_f32_e32 v68, v68
	v_exp_f32_e32 v69, v69
	v_exp_f32_e32 v70, v70
	v_exp_f32_e32 v71, v71
	s_waitcnt lgkmcnt(5)
	v_mfma_f32_32x32x16_bf16 v[48:63], v[128:131], v[148:151], v[48:63]
	ds_read_b128 v[128:131], v209 offset:58368
	v_cvt_pk_bf16_f32 v112, v64, v65
	v_cvt_pk_bf16_f32 v113, v66, v67
	v_cvt_pk_bf16_f32 v114, v68, v69
	v_cvt_pk_bf16_f32 v115, v70, v71
	s_waitcnt lgkmcnt(5)
	v_mfma_f32_32x32x16_bf16 v[16:31], v[132:135], v[124:127], v[16:31]
	ds_read_b128 v[132:135], v209 offset:62976
	v_exp_f32_e32 v72, v72
	v_exp_f32_e32 v73, v73
	v_exp_f32_e32 v74, v74
	v_exp_f32_e32 v75, v75
	s_waitcnt lgkmcnt(5)
	v_mfma_f32_32x32x16_bf16 v[32:47], v[136:139], v[124:127], v[32:47]
	ds_read_b128 v[136:139], v209 offset:58400
	v_exp_f32_e32 v76, v76
	v_exp_f32_e32 v77, v77
	v_exp_f32_e32 v78, v78
	v_exp_f32_e32 v79, v79
	s_waitcnt lgkmcnt(5)
	v_mfma_f32_32x32x16_bf16 v[48:63], v[140:143], v[152:155], v[48:63]
	ds_read_b128 v[140:143], v209 offset:63008
	v_cvt_pk_bf16_f32 v116, v72, v73
	v_cvt_pk_bf16_f32 v117, v74, v75
	v_cvt_pk_bf16_f32 v118, v76, v77
	v_cvt_pk_bf16_f32 v119, v78, v79
	s_waitcnt lgkmcnt(5)
	v_mfma_f32_32x32x16_bf16 v[48:63], v[188:191], v[156:159], v[48:63]
	v_add_f32_e32 v92, v108, v92
	v_add_f32_e32 v232, v232, v92
	v_add_f32_e32 v93, v109, v93
	v_add_f32_e32 v233, v233, v93
	s_waitcnt lgkmcnt(4)
	v_mfma_f32_32x32x16_bf16 v[48:63], v[168:171], v[160:163], v[48:63]
	v_add_f32_e32 v94, v110, v94
	v_add_f32_e32 v230, v230, v94
	v_add_f32_e32 v95, v111, v95
	v_add_f32_e32 v231, v231, v95
	s_waitcnt lgkmcnt(4)
	s_barrier
	ds_read_b128 v[188:191], v187 offset:0
	ds_read_b128 v[168:171], v187 offset:32
	s_waitcnt lgkmcnt(5)
	v_mfma_f32_32x32x16_bf16 v[16:31], v[128:131], v[112:115], v[16:31]
	ds_read_b128 v[220:223], v187 offset:64
	s_waitcnt vmcnt(0)
	ds_write_b128 v211, v[176:179] offset:22528
	s_and_saveexec_b64 s[42:43], s[36:37]
	s_cbranch_execz .Lattn_fx_w4
	ds_write_b128 v186, v[172:175] offset:22528
; #define ATT_LOAD(t) do { sk0 = *(const u32x4*)(kp0 + (size_t)(t) * 64 * 768); if (has1) sk1 = *(const u32x4*)(kp1 + (size_t)(t) * 64 * 768); sv = *(const u32x4*)(vp + (t) * 64); } while (0)
; #define ATT_STORE(boff) do { *(LAS u32x4*)(lds + (boff) + kw0) = sk0; if (has1) *(LAS u32x4*)(lds + (boff) + kw1) = sk1; *(LAS u32x4*)(lds + (boff) + vw) = sv; } while (0)
; template <bool FIXED> __device__ __forceinline__ void attn_unit(unsigned char* ws, LAS unsigned char* lds, int b, int h, int qb, const int tid, const float sbound) {
;     ...
;     ATT_LOAD(0); ATT_STORE(0); ATT_LOAD(1); ATT_STORE(ABUF); ATT_LOAD(2);
;     __syncthreads();
;     const int pi_r = (r32 & ~12) | ((r32 & 4) << 1) | ((r32 & 8) >> 1);
;     const int kro = pi_r * AKP + hi * 16, vro = AKB + r32 * AVP + hi * 16;
;     f32x16 o0 = {}, o1 = {}, negm = {};
;     float mref = 0.f, lsum = 0.f;
;     ...
;     if constexpr (FIXED) { for (int kt = 0; kt < SEQ / 64; kt += 2) { ATT_STEP_FIXED(pA0, pA1, pB0, pB1, kt); ATT_STEP_FIXED(pB0, pB1, pA0, pA1, kt + 1); }
.Lattn_fx_w4:
	s_or_b64 exec, exec, s[42:43]
	ds_write_b128 v208, v[180:183] offset:35840
	v_exp_f32_e32 v48, v48
	v_exp_f32_e32 v49, v49
	v_exp_f32_e32 v50, v50
	v_exp_f32_e32 v51, v51
	s_waitcnt lgkmcnt(7)
	v_mfma_f32_32x32x16_bf16 v[32:47], v[132:135], v[112:115], v[32:47]
	ds_read_b128 v[128:131], v187 offset:96
	global_load_dwordx4 v[176:179], v212, s[6:7]
	s_and_saveexec_b64 s[42:43], s[36:37]
	s_cbranch_execz .Lattn_fx_g5
	global_load_dwordx4 v[172:175], v214, s[6:7]
.Lattn_fx_g5:
	s_or_b64 exec, exec, s[42:43]
	global_load_dwordx4 v[180:183], v204, s[40:41]
	s_add_u32 s6, s6, 0x18000
	s_addc_u32 s7, s7, 0
	s_add_u32 s40, s40, 0x80
	s_addc_u32 s41, s41, 0
	v_exp_f32_e32 v52, v52
	v_exp_f32_e32 v53, v53
	v_exp_f32_e32 v54, v54
	v_exp_f32_e32 v55, v55
	s_waitcnt lgkmcnt(7)
	v_mfma_f32_32x32x16_bf16 v[16:31], v[136:139], v[116:119], v[16:31]
	ds_read_b128 v[132:135], v187 offset:128
	v_cvt_pk_bf16_f32 v120, v48, v49
	v_cvt_pk_bf16_f32 v121, v50, v51
	v_cvt_pk_bf16_f32 v122, v52, v53
	v_cvt_pk_bf16_f32 v123, v54, v55
	s_waitcnt lgkmcnt(7)
	v_mfma_f32_32x32x16_bf16 v[32:47], v[140:143], v[116:119], v[32:47]
	ds_read_b128 v[136:139], v187 offset:160
	v_exp_f32_e32 v56, v56
	v_exp_f32_e32 v57, v57
	v_exp_f32_e32 v58, v58
	v_exp_f32_e32 v59, v59
	s_waitcnt lgkmcnt(7)
	v_mfma_f32_32x32x16_bf16 v[96:111], v[188:191], v[164:167], v[0:15]
	ds_read_b128 v[140:143], v209 offset:58432
	v_exp_f32_e32 v60, v60
	v_exp_f32_e32 v61, v61
	v_exp_f32_e32 v62, v62
	v_exp_f32_e32 v63, v63
	s_waitcnt lgkmcnt(7)
	v_mfma_f32_32x32x16_bf16 v[96:111], v[168:171], v[144:147], v[96:111]
	ds_read_b128 v[188:191], v209 offset:63040
	v_cvt_pk_bf16_f32 v124, v56, v57
	v_cvt_pk_bf16_f32 v125, v58, v59
	v_cvt_pk_bf16_f32 v126, v60, v61
	v_cvt_pk_bf16_f32 v127, v62, v63
	s_waitcnt lgkmcnt(7)
	v_mfma_f32_32x32x16_bf16 v[96:111], v[220:223], v[148:151], v[96:111]
	ds_read_b128 v[168:171], v187 offset:6656
	v_add_f32_e32 v48, v64, v48
	v_add_f32_e32 v244, v244, v48
	v_add_f32_e32 v49, v65, v49
	v_add_f32_e32 v245, v245, v49
	s_waitcnt lgkmcnt(5)
	v_mfma_f32_32x32x16_bf16 v[96:111], v[128:131], v[152:155], v[96:111]
	ds_read_b128 v[220:223], v187 offset:6688
	v_add_f32_e32 v50, v66, v50
	v_add_f32_e32 v242, v242, v50
	v_add_f32_e32 v51, v67, v51
	v_add_f32_e32 v243, v243, v51
	s_waitcnt lgkmcnt(5)
	v_mfma_f32_32x32x16_bf16 v[96:111], v[132:135], v[156:159], v[96:111]
	ds_read_b128 v[128:131], v187 offset:6720
	v_add_f32_e32 v52, v68, v52
	v_add_f32_e32 v240, v240, v52
	v_add_f32_e32 v53, v69, v53
	v_add_f32_e32 v241, v241, v53
	s_waitcnt lgkmcnt(5)
	v_mfma_f32_32x32x16_bf16 v[96:111], v[136:139], v[160:163], v[96:111]
	ds_read_b128 v[132:135], v209 offset:58464
	v_add_f32_e32 v54, v70, v54
	v_add_f32_e32 v238, v238, v54
	v_add_f32_e32 v55, v71, v55
	v_add_f32_e32 v239, v239, v55
	s_waitcnt lgkmcnt(5)
	v_mfma_f32_32x32x16_bf16 v[16:31], v[140:143], v[120:123], v[16:31]
	ds_read_b128 v[136:139], v209 offset:63072
	v_add_f32_e32 v56, v72, v56
	v_add_f32_e32 v236, v236, v56
	v_add_f32_e32 v57, v73, v57
	v_add_f32_e32 v237, v237, v57
	s_waitcnt lgkmcnt(5)
	v_mfma_f32_32x32x16_bf16 v[32:47], v[188:191], v[120:123], v[32:47]
	ds_read_b128 v[140:143], v187 offset:6752
	v_add_f32_e32 v58, v74, v58
	v_add_f32_e32 v234, v234, v58
	v_add_f32_e32 v59, v75, v59
	v_add_f32_e32 v235, v235, v59
	s_waitcnt lgkmcnt(5)
	v_mfma_f32_32x32x16_bf16 v[80:95], v[168:171], v[164:167], v[0:15]
	ds_read_b128 v[188:191], v187 offset:6784
	v_exp_f32_e32 v96, v96
	v_exp_f32_e32 v97, v97
	v_exp_f32_e32 v98, v98
	v_exp_f32_e32 v99, v99
	s_waitcnt lgkmcnt(5)
	v_mfma_f32_32x32x16_bf16 v[80:95], v[220:223], v[144:147], v[80:95]
	ds_read_b128 v[168:171], v187 offset:6816
	v_exp_f32_e32 v100, v100
	v_exp_f32_e32 v101, v101
	v_exp_f32_e32 v102, v102
	v_exp_f32_e32 v103, v103
	s_waitcnt lgkmcnt(5)
	v_mfma_f32_32x32x16_bf16 v[80:95], v[128:131], v[148:151], v[80:95]
	ds_read_b128 v[128:131], v209 offset:13312
	v_cvt_pk_bf16_f32 v112, v96, v97
	v_cvt_pk_bf16_f32 v113, v98, v99
	v_cvt_pk_bf16_f32 v114, v100, v101
	v_cvt_pk_bf16_f32 v115, v102, v103
	s_waitcnt lgkmcnt(5)
	v_mfma_f32_32x32x16_bf16 v[16:31], v[132:135], v[124:127], v[16:31]
	ds_read_b128 v[132:135], v209 offset:17920
	v_exp_f32_e32 v104, v104
	v_exp_f32_e32 v105, v105
	v_exp_f32_e32 v106, v106
	v_exp_f32_e32 v107, v107
	s_waitcnt lgkmcnt(5)
	v_mfma_f32_32x32x16_bf16 v[32:47], v[136:139], v[124:127], v[32:47]
	ds_read_b128 v[136:139], v209 offset:13344
	v_exp_f32_e32 v108, v108
	v_exp_f32_e32 v109, v109
	v_exp_f32_e32 v110, v110
	v_exp_f32_e32 v111, v111
	s_waitcnt lgkmcnt(5)
	v_mfma_f32_32x32x16_bf16 v[80:95], v[140:143], v[152:155], v[80:95]
	ds_read_b128 v[140:143], v209 offset:17952
	v_cvt_pk_bf16_f32 v116, v104, v105
	v_cvt_pk_bf16_f32 v117, v106, v107
	v_cvt_pk_bf16_f32 v118, v108, v109
	v_cvt_pk_bf16_f32 v119, v110, v111
	s_waitcnt lgkmcnt(5)
	v_mfma_f32_32x32x16_bf16 v[80:95], v[188:191], v[156:159], v[80:95]
	v_add_f32_e32 v60, v76, v60
	v_add_f32_e32 v232, v232, v60
	v_add_f32_e32 v61, v77, v61
	v_add_f32_e32 v233, v233, v61
	s_waitcnt lgkmcnt(4)
	v_mfma_f32_32x32x16_bf16 v[80:95], v[168:171], v[160:163], v[80:95]
	v_add_f32_e32 v62, v78, v62
	v_add_f32_e32 v230, v230, v62
	v_add_f32_e32 v63, v79, v63
	v_add_f32_e32 v231, v231, v63
	s_waitcnt lgkmcnt(4)
	s_barrier
	ds_read_b128 v[188:191], v187 offset:22528
	ds_read_b128 v[168:171], v187 offset:22560
	s_waitcnt lgkmcnt(5)
	v_mfma_f32_32x32x16_bf16 v[16:31], v[128:131], v[112:115], v[16:31]
	ds_read_b128 v[220:223], v187 offset:22592
	s_waitcnt vmcnt(0)
	ds_write_b128 v211, v[176:179] offset:45056
	s_and_saveexec_b64 s[42:43], s[36:37]
	s_cbranch_execz .Lattn_fx_w6
	ds_write_b128 v186, v[172:175] offset:45056
; #define ATT_LOAD(t) do { sk0 = *(const u32x4*)(kp0 + (size_t)(t) * 64 * 768); if (has1) sk1 = *(const u32x4*)(kp1 + (size_t)(t) * 64 * 768); sv = *(const u32x4*)(vp + (t) * 64); } while (0)
; #define ATT_STORE(boff) do { *(LAS u32x4*)(lds + (boff) + kw0) = sk0; if (has1) *(LAS u32x4*)(lds + (boff) + kw1) = sk1; *(LAS u32x4*)(lds + (boff) + vw) = sv; } while (0)
; template <bool FIXED> __device__ __forceinline__ void attn_unit(unsigned char* ws, LAS unsigned char* lds, int b, int h, int qb, const int tid, const float sbound) {
;     ...
;     ATT_LOAD(0); ATT_STORE(0); ATT_LOAD(1); ATT_STORE(ABUF); ATT_LOAD(2);
;     __syncthreads();
;     const int pi_r = (r32 & ~12) | ((r32 & 4) << 1) | ((r32 & 8) >> 1);
;     const int kro = pi_r * AKP + hi * 16, vro = AKB + r32 * AVP + hi * 16;
;     f32x16 o0 = {}, o1 = {}, negm = {};
;     float mref = 0.f, lsum = 0.f;
;     ...
;     if constexpr (FIXED) { for (int kt = 0; kt < SEQ / 64; kt += 2) { ATT_STEP_FIXED(pA0, pA1, pB0, pB1, kt); ATT_STEP_FIXED(pB0, pB1, pA0, pA1, kt + 1); }
.Lattn_fx_w6:
	s_or_b64 exec, exec, s[42:43]
	ds_write_b128 v208, v[180:183] offset:58368
	v_exp_f32_e32 v80, v80
	v_exp_f32_e32 v81, v81
	v_exp_f32_e32 v82, v82
	v_exp_f32_e32 v83, v83
	s_waitcnt lgkmcnt(7)
	v_mfma_f32_32x32x16_bf16 v[32:47], v[132:135], v[112:115], v[32:47]
	ds_read_b128 v[128:131], v187 offset:22624
	global_load_dwordx4 v[176:179], v212, s[6:7]
	s_and_saveexec_b64 s[42:43], s[36:37]
	s_cbranch_execz .Lattn_fx_g7
	global_load_dwordx4 v[172:175], v214, s[6:7]
.Lattn_fx_g7:
	s_or_b64 exec, exec, s[42:43]
	global_load_dwordx4 v[180:183], v204, s[40:41]
	s_add_u32 s6, s6, 0x18000
	s_addc_u32 s7, s7, 0
	s_add_u32 s40, s40, 0x80
	s_addc_u32 s41, s41, 0
	v_exp_f32_e32 v84, v84
	v_exp_f32_e32 v85, v85
	v_exp_f32_e32 v86, v86
	v_exp_f32_e32 v87, v87
	s_waitcnt lgkmcnt(7)
	v_mfma_f32_32x32x16_bf16 v[16:31], v[136:139], v[116:119], v[16:31]
	ds_read_b128 v[132:135], v187 offset:22656
	v_cvt_pk_bf16_f32 v120, v80, v81
	v_cvt_pk_bf16_f32 v121, v82, v83
	v_cvt_pk_bf16_f32 v122, v84, v85
	v_cvt_pk_bf16_f32 v123, v86, v87
	s_waitcnt lgkmcnt(7)
	v_mfma_f32_32x32x16_bf16 v[32:47], v[140:143], v[116:119], v[32:47]
	ds_read_b128 v[136:139], v187 offset:22688
	v_exp_f32_e32 v88, v88
	v_exp_f32_e32 v89, v89
	v_exp_f32_e32 v90, v90
	v_exp_f32_e32 v91, v91
	s_waitcnt lgkmcnt(7)
	v_mfma_f32_32x32x16_bf16 v[64:79], v[188:191], v[164:167], v[0:15]
	ds_read_b128 v[140:143], v209 offset:13376
	v_exp_f32_e32 v92, v92
	v_exp_f32_e32 v93, v93
	v_exp_f32_e32 v94, v94
	v_exp_f32_e32 v95, v95
	s_waitcnt lgkmcnt(7)
	v_mfma_f32_32x32x16_bf16 v[64:79], v[168:171], v[144:147], v[64:79]
	ds_read_b128 v[188:191], v209 offset:17984
	v_cvt_pk_bf16_f32 v124, v88, v89
	v_cvt_pk_bf16_f32 v125, v90, v91
	v_cvt_pk_bf16_f32 v126, v92, v93
	v_cvt_pk_bf16_f32 v127, v94, v95
	s_waitcnt lgkmcnt(7)
	v_mfma_f32_32x32x16_bf16 v[64:79], v[220:223], v[148:151], v[64:79]
	ds_read_b128 v[168:171], v187 offset:29184
	v_add_f32_e32 v80, v96, v80
	v_add_f32_e32 v244, v244, v80
	v_add_f32_e32 v81, v97, v81
	v_add_f32_e32 v245, v245, v81
	s_waitcnt lgkmcnt(5)
	v_mfma_f32_32x32x16_bf16 v[64:79], v[128:131], v[152:155], v[64:79]
	ds_read_b128 v[220:223], v187 offset:29216
	v_add_f32_e32 v82, v98, v82
	v_add_f32_e32 v242, v242, v82
	v_add_f32_e32 v83, v99, v83
	v_add_f32_e32 v243, v243, v83
	s_waitcnt lgkmcnt(5)
	v_mfma_f32_32x32x16_bf16 v[64:79], v[132:135], v[156:159], v[64:79]
	ds_read_b128 v[128:131], v187 offset:29248
	v_add_f32_e32 v84, v100, v84
	v_add_f32_e32 v240, v240, v84
	v_add_f32_e32 v85, v101, v85
	v_add_f32_e32 v241, v241, v85
	s_waitcnt lgkmcnt(5)
	v_mfma_f32_32x32x16_bf16 v[64:79], v[136:139], v[160:163], v[64:79]
	ds_read_b128 v[132:135], v209 offset:13408
	v_add_f32_e32 v86, v102, v86
	v_add_f32_e32 v238, v238, v86
	v_add_f32_e32 v87, v103, v87
	v_add_f32_e32 v239, v239, v87
	s_waitcnt lgkmcnt(5)
	v_mfma_f32_32x32x16_bf16 v[16:31], v[140:143], v[120:123], v[16:31]
	ds_read_b128 v[136:139], v209 offset:18016
	v_add_f32_e32 v88, v104, v88
	v_add_f32_e32 v236, v236, v88
	v_add_f32_e32 v89, v105, v89
	v_add_f32_e32 v237, v237, v89
	s_waitcnt lgkmcnt(5)
	v_mfma_f32_32x32x16_bf16 v[32:47], v[188:191], v[120:123], v[32:47]
	ds_read_b128 v[140:143], v187 offset:29280
	v_add_f32_e32 v90, v106, v90
	v_add_f32_e32 v234, v234, v90
	v_add_f32_e32 v91, v107, v91
	v_add_f32_e32 v235, v235, v91
	s_waitcnt lgkmcnt(5)
	v_mfma_f32_32x32x16_bf16 v[48:63], v[168:171], v[164:167], v[0:15]
	ds_read_b128 v[188:191], v187 offset:29312
	v_exp_f32_e32 v64, v64
	v_exp_f32_e32 v65, v65
	v_exp_f32_e32 v66, v66
	v_exp_f32_e32 v67, v67
	s_waitcnt lgkmcnt(5)
	v_mfma_f32_32x32x16_bf16 v[48:63], v[220:223], v[144:147], v[48:63]
	ds_read_b128 v[168:171], v187 offset:29344
	v_exp_f32_e32 v68, v68
	v_exp_f32_e32 v69, v69
	v_exp_f32_e32 v70, v70
	v_exp_f32_e32 v71, v71
	s_waitcnt lgkmcnt(5)
	v_mfma_f32_32x32x16_bf16 v[48:63], v[128:131], v[148:151], v[48:63]
	ds_read_b128 v[128:131], v209 offset:35840
	v_cvt_pk_bf16_f32 v112, v64, v65
	v_cvt_pk_bf16_f32 v113, v66, v67
	v_cvt_pk_bf16_f32 v114, v68, v69
	v_cvt_pk_bf16_f32 v115, v70, v71
	s_waitcnt lgkmcnt(5)
	v_mfma_f32_32x32x16_bf16 v[16:31], v[132:135], v[124:127], v[16:31]
	ds_read_b128 v[132:135], v209 offset:40448
	v_exp_f32_e32 v72, v72
	v_exp_f32_e32 v73, v73
	v_exp_f32_e32 v74, v74
	v_exp_f32_e32 v75, v75
	s_waitcnt lgkmcnt(5)
	v_mfma_f32_32x32x16_bf16 v[32:47], v[136:139], v[124:127], v[32:47]
	ds_read_b128 v[136:139], v209 offset:35872
	v_exp_f32_e32 v76, v76
	v_exp_f32_e32 v77, v77
	v_exp_f32_e32 v78, v78
	v_exp_f32_e32 v79, v79
	s_waitcnt lgkmcnt(5)
	v_mfma_f32_32x32x16_bf16 v[48:63], v[140:143], v[152:155], v[48:63]
	ds_read_b128 v[140:143], v209 offset:40480
	v_cvt_pk_bf16_f32 v116, v72, v73
	v_cvt_pk_bf16_f32 v117, v74, v75
	v_cvt_pk_bf16_f32 v118, v76, v77
	v_cvt_pk_bf16_f32 v119, v78, v79
	s_waitcnt lgkmcnt(5)
	v_mfma_f32_32x32x16_bf16 v[48:63], v[188:191], v[156:159], v[48:63]
	v_add_f32_e32 v92, v108, v92
	v_add_f32_e32 v232, v232, v92
	v_add_f32_e32 v93, v109, v93
	v_add_f32_e32 v233, v233, v93
	s_waitcnt lgkmcnt(4)
	v_mfma_f32_32x32x16_bf16 v[48:63], v[168:171], v[160:163], v[48:63]
	v_add_f32_e32 v94, v110, v94
	v_add_f32_e32 v230, v230, v94
	v_add_f32_e32 v95, v111, v95
	v_add_f32_e32 v231, v231, v95
	s_waitcnt lgkmcnt(4)
	s_barrier
	ds_read_b128 v[188:191], v187 offset:45056
	ds_read_b128 v[168:171], v187 offset:45088
	s_waitcnt lgkmcnt(5)
	v_mfma_f32_32x32x16_bf16 v[16:31], v[128:131], v[112:115], v[16:31]
	ds_read_b128 v[220:223], v187 offset:45120
	s_waitcnt vmcnt(0)
	ds_write_b128 v211, v[176:179] offset:0
	s_and_saveexec_b64 s[42:43], s[36:37]
	s_cbranch_execz .Lattn_fx_w8
	ds_write_b128 v186, v[172:175] offset:0
; #define ATT_LOAD(t) do { sk0 = *(const u32x4*)(kp0 + (size_t)(t) * 64 * 768); if (has1) sk1 = *(const u32x4*)(kp1 + (size_t)(t) * 64 * 768); sv = *(const u32x4*)(vp + (t) * 64); } while (0)
; #define ATT_STORE(boff) do { *(LAS u32x4*)(lds + (boff) + kw0) = sk0; if (has1) *(LAS u32x4*)(lds + (boff) + kw1) = sk1; *(LAS u32x4*)(lds + (boff) + vw) = sv; } while (0)
; template <bool FIXED> __device__ __forceinline__ void attn_unit(unsigned char* ws, LAS unsigned char* lds, int b, int h, int qb, const int tid, const float sbound) {
;     ...
;     ATT_LOAD(0); ATT_STORE(0); ATT_LOAD(1); ATT_STORE(ABUF); ATT_LOAD(2);
;     __syncthreads();
;     const int pi_r = (r32 & ~12) | ((r32 & 4) << 1) | ((r32 & 8) >> 1);
;     const int kro = pi_r * AKP + hi * 16, vro = AKB + r32 * AVP + hi * 16;
;     f32x16 o0 = {}, o1 = {}, negm = {};
;     float mref = 0.f, lsum = 0.f;
;     ...
;     if constexpr (FIXED) { for (int kt = 0; kt < SEQ / 64; kt += 2) { ATT_STEP_FIXED(pA0, pA1, pB0, pB1, kt); ATT_STEP_FIXED(pB0, pB1, pA0, pA1, kt + 1); }
.Lattn_fx_w8:
	s_or_b64 exec, exec, s[42:43]
	ds_write_b128 v208, v[180:183] offset:13312
	v_exp_f32_e32 v48, v48
	v_exp_f32_e32 v49, v49
	v_exp_f32_e32 v50, v50
	v_exp_f32_e32 v51, v51
	s_waitcnt lgkmcnt(7)
	v_mfma_f32_32x32x16_bf16 v[32:47], v[132:135], v[112:115], v[32:47]
	ds_read_b128 v[128:131], v187 offset:45152
	global_load_dwordx4 v[176:179], v212, s[6:7]
	s_and_saveexec_b64 s[42:43], s[36:37]
	s_cbranch_execz .Lattn_fx_g9
	global_load_dwordx4 v[172:175], v214, s[6:7]
.Lattn_fx_g9:
	s_or_b64 exec, exec, s[42:43]
	global_load_dwordx4 v[180:183], v204, s[40:41]
	s_add_u32 s6, s6, 0x18000
	s_addc_u32 s7, s7, 0
	s_add_u32 s40, s40, 0x80
	s_addc_u32 s41, s41, 0
	v_exp_f32_e32 v52, v52
	v_exp_f32_e32 v53, v53
	v_exp_f32_e32 v54, v54
	v_exp_f32_e32 v55, v55
	s_waitcnt lgkmcnt(7)
	v_mfma_f32_32x32x16_bf16 v[16:31], v[136:139], v[116:119], v[16:31]
	ds_read_b128 v[132:135], v187 offset:45184
	v_cvt_pk_bf16_f32 v120, v48, v49
	v_cvt_pk_bf16_f32 v121, v50, v51
	v_cvt_pk_bf16_f32 v122, v52, v53
	v_cvt_pk_bf16_f32 v123, v54, v55
	s_waitcnt lgkmcnt(7)
	v_mfma_f32_32x32x16_bf16 v[32:47], v[140:143], v[116:119], v[32:47]
	ds_read_b128 v[136:139], v187 offset:45216
	v_exp_f32_e32 v56, v56
	v_exp_f32_e32 v57, v57
	v_exp_f32_e32 v58, v58
	v_exp_f32_e32 v59, v59
	s_waitcnt lgkmcnt(7)
	v_mfma_f32_32x32x16_bf16 v[96:111], v[188:191], v[164:167], v[0:15]
	ds_read_b128 v[140:143], v209 offset:35904
	v_exp_f32_e32 v60, v60
	v_exp_f32_e32 v61, v61
	v_exp_f32_e32 v62, v62
	v_exp_f32_e32 v63, v63
	s_waitcnt lgkmcnt(7)
	v_mfma_f32_32x32x16_bf16 v[96:111], v[168:171], v[144:147], v[96:111]
	ds_read_b128 v[188:191], v209 offset:40512
	v_cvt_pk_bf16_f32 v124, v56, v57
	v_cvt_pk_bf16_f32 v125, v58, v59
	v_cvt_pk_bf16_f32 v126, v60, v61
	v_cvt_pk_bf16_f32 v127, v62, v63
	s_waitcnt lgkmcnt(7)
	v_mfma_f32_32x32x16_bf16 v[96:111], v[220:223], v[148:151], v[96:111]
	ds_read_b128 v[168:171], v187 offset:51712
	v_add_f32_e32 v48, v64, v48
	v_add_f32_e32 v244, v244, v48
	v_add_f32_e32 v49, v65, v49
	v_add_f32_e32 v245, v245, v49
	s_waitcnt lgkmcnt(5)
	v_mfma_f32_32x32x16_bf16 v[96:111], v[128:131], v[152:155], v[96:111]
	ds_read_b128 v[220:223], v187 offset:51744
	v_add_f32_e32 v50, v66, v50
	v_add_f32_e32 v242, v242, v50
	v_add_f32_e32 v51, v67, v51
	v_add_f32_e32 v243, v243, v51
	s_waitcnt lgkmcnt(5)
	v_mfma_f32_32x32x16_bf16 v[96:111], v[132:135], v[156:159], v[96:111]
	ds_read_b128 v[128:131], v187 offset:51776
	v_add_f32_e32 v52, v68, v52
	v_add_f32_e32 v240, v240, v52
	v_add_f32_e32 v53, v69, v53
	v_add_f32_e32 v241, v241, v53
	s_waitcnt lgkmcnt(5)
	v_mfma_f32_32x32x16_bf16 v[96:111], v[136:139], v[160:163], v[96:111]
	ds_read_b128 v[132:135], v209 offset:35936
	v_add_f32_e32 v54, v70, v54
	v_add_f32_e32 v238, v238, v54
	v_add_f32_e32 v55, v71, v55
	v_add_f32_e32 v239, v239, v55
	s_waitcnt lgkmcnt(5)
	v_mfma_f32_32x32x16_bf16 v[16:31], v[140:143], v[120:123], v[16:31]
	ds_read_b128 v[136:139], v209 offset:40544
	v_add_f32_e32 v56, v72, v56
	v_add_f32_e32 v236, v236, v56
	v_add_f32_e32 v57, v73, v57
	v_add_f32_e32 v237, v237, v57
	s_waitcnt lgkmcnt(5)
	v_mfma_f32_32x32x16_bf16 v[32:47], v[188:191], v[120:123], v[32:47]
	ds_read_b128 v[140:143], v187 offset:51808
	v_add_f32_e32 v58, v74, v58
	v_add_f32_e32 v234, v234, v58
	v_add_f32_e32 v59, v75, v59
	v_add_f32_e32 v235, v235, v59
	s_waitcnt lgkmcnt(5)
	v_mfma_f32_32x32x16_bf16 v[80:95], v[168:171], v[164:167], v[0:15]
	ds_read_b128 v[188:191], v187 offset:51840
	v_exp_f32_e32 v96, v96
	v_exp_f32_e32 v97, v97
	v_exp_f32_e32 v98, v98
	v_exp_f32_e32 v99, v99
	s_waitcnt lgkmcnt(5)
	v_mfma_f32_32x32x16_bf16 v[80:95], v[220:223], v[144:147], v[80:95]
	ds_read_b128 v[168:171], v187 offset:51872
	v_exp_f32_e32 v100, v100
	v_exp_f32_e32 v101, v101
	v_exp_f32_e32 v102, v102
	v_exp_f32_e32 v103, v103
	s_waitcnt lgkmcnt(5)
	v_mfma_f32_32x32x16_bf16 v[80:95], v[128:131], v[148:151], v[80:95]
	ds_read_b128 v[128:131], v209 offset:58368
	v_cvt_pk_bf16_f32 v112, v96, v97
	v_cvt_pk_bf16_f32 v113, v98, v99
	v_cvt_pk_bf16_f32 v114, v100, v101
	v_cvt_pk_bf16_f32 v115, v102, v103
	s_waitcnt lgkmcnt(5)
	v_mfma_f32_32x32x16_bf16 v[16:31], v[132:135], v[124:127], v[16:31]
	ds_read_b128 v[132:135], v209 offset:62976
	v_exp_f32_e32 v104, v104
	v_exp_f32_e32 v105, v105
	v_exp_f32_e32 v106, v106
	v_exp_f32_e32 v107, v107
	s_waitcnt lgkmcnt(5)
	v_mfma_f32_32x32x16_bf16 v[32:47], v[136:139], v[124:127], v[32:47]
	ds_read_b128 v[136:139], v209 offset:58400
	v_exp_f32_e32 v108, v108
	v_exp_f32_e32 v109, v109
	v_exp_f32_e32 v110, v110
	v_exp_f32_e32 v111, v111
	s_waitcnt lgkmcnt(5)
	v_mfma_f32_32x32x16_bf16 v[80:95], v[140:143], v[152:155], v[80:95]
	ds_read_b128 v[140:143], v209 offset:63008
	v_cvt_pk_bf16_f32 v116, v104, v105
	v_cvt_pk_bf16_f32 v117, v106, v107
	v_cvt_pk_bf16_f32 v118, v108, v109
	v_cvt_pk_bf16_f32 v119, v110, v111
	s_waitcnt lgkmcnt(5)
	v_mfma_f32_32x32x16_bf16 v[80:95], v[188:191], v[156:159], v[80:95]
	v_add_f32_e32 v60, v76, v60
	v_add_f32_e32 v232, v232, v60
	v_add_f32_e32 v61, v77, v61
	v_add_f32_e32 v233, v233, v61
	s_waitcnt lgkmcnt(4)
	v_mfma_f32_32x32x16_bf16 v[80:95], v[168:171], v[160:163], v[80:95]
	v_add_f32_e32 v62, v78, v62
	v_add_f32_e32 v230, v230, v62
	v_add_f32_e32 v63, v79, v63
	v_add_f32_e32 v231, v231, v63
	s_waitcnt lgkmcnt(4)
	s_barrier
	ds_read_b128 v[188:191], v187 offset:0
	ds_read_b128 v[168:171], v187 offset:32
	s_waitcnt lgkmcnt(5)
	v_mfma_f32_32x32x16_bf16 v[16:31], v[128:131], v[112:115], v[16:31]
	ds_read_b128 v[220:223], v187 offset:64
	s_waitcnt vmcnt(0)
	ds_write_b128 v211, v[176:179] offset:22528
	s_and_saveexec_b64 s[42:43], s[36:37]
	s_cbranch_execz .Lattn_fx_w10
	ds_write_b128 v186, v[172:175] offset:22528
; template <bool FIXED> __device__ __forceinline__ void attn_unit(unsigned char* ws, LAS unsigned char* lds, int b, int h, int qb, const int tid, const float sbound) {
;     ...
;     if constexpr (FIXED) { for (int kt = 0; kt < SEQ / 64; kt += 2) { ATT_STEP_FIXED(pA0, pA1, pB0, pB1, kt); ATT_STEP_FIXED(pB0, pB1, pA0, pA1, kt + 1); }
.Lattn_fx_w10:
	s_or_b64 exec, exec, s[42:43]
	ds_write_b128 v208, v[180:183] offset:35840
	v_exp_f32_e32 v80, v80
	v_exp_f32_e32 v81, v81
	v_exp_f32_e32 v82, v82
	v_exp_f32_e32 v83, v83
	s_waitcnt lgkmcnt(7)
	v_mfma_f32_32x32x16_bf16 v[32:47], v[132:135], v[112:115], v[32:47]
	ds_read_b128 v[128:131], v187 offset:96
	s_cmp_eq_u32 s14, 20
	s_cbranch_scc1 .Lattn_fx_skipld
	global_load_dwordx4 v[176:179], v212, s[6:7]
	s_and_saveexec_b64 s[42:43], s[36:37]
	s_cbranch_execz .Lattn_fx_g11
	global_load_dwordx4 v[172:175], v214, s[6:7]
.Lattn_fx_g11:
	s_or_b64 exec, exec, s[42:43]
	global_load_dwordx4 v[180:183], v204, s[40:41]
	s_add_u32 s6, s6, 0x18000
	s_addc_u32 s7, s7, 0
	s_add_u32 s40, s40, 0x80
	s_addc_u32 s41, s41, 0
.Lattn_fx_skipld:
	v_exp_f32_e32 v84, v84
	v_exp_f32_e32 v85, v85
	v_exp_f32_e32 v86, v86
	v_exp_f32_e32 v87, v87
	s_waitcnt lgkmcnt(7)
	v_mfma_f32_32x32x16_bf16 v[16:31], v[136:139], v[116:119], v[16:31]
	ds_read_b128 v[132:135], v187 offset:128
	v_cvt_pk_bf16_f32 v120, v80, v81
	v_cvt_pk_bf16_f32 v121, v82, v83
	v_cvt_pk_bf16_f32 v122, v84, v85
	v_cvt_pk_bf16_f32 v123, v86, v87
	s_waitcnt lgkmcnt(7)
	v_mfma_f32_32x32x16_bf16 v[32:47], v[140:143], v[116:119], v[32:47]
	ds_read_b128 v[136:139], v187 offset:160
	v_exp_f32_e32 v88, v88
	v_exp_f32_e32 v89, v89
	v_exp_f32_e32 v90, v90
	v_exp_f32_e32 v91, v91
	s_waitcnt lgkmcnt(7)
	v_mfma_f32_32x32x16_bf16 v[64:79], v[188:191], v[164:167], v[0:15]
	ds_read_b128 v[140:143], v209 offset:58432
	v_exp_f32_e32 v92, v92
	v_exp_f32_e32 v93, v93
	v_exp_f32_e32 v94, v94
	v_exp_f32_e32 v95, v95
	s_waitcnt lgkmcnt(7)
	v_mfma_f32_32x32x16_bf16 v[64:79], v[168:171], v[144:147], v[64:79]
	ds_read_b128 v[188:191], v209 offset:63040
	v_cvt_pk_bf16_f32 v124, v88, v89
	v_cvt_pk_bf16_f32 v125, v90, v91
	v_cvt_pk_bf16_f32 v126, v92, v93
	v_cvt_pk_bf16_f32 v127, v94, v95
	s_waitcnt lgkmcnt(7)
	v_mfma_f32_32x32x16_bf16 v[64:79], v[220:223], v[148:151], v[64:79]
	ds_read_b128 v[168:171], v187 offset:6656
	v_add_f32_e32 v80, v96, v80
	v_add_f32_e32 v244, v244, v80
	v_add_f32_e32 v81, v97, v81
	v_add_f32_e32 v245, v245, v81
	s_waitcnt lgkmcnt(5)
	v_mfma_f32_32x32x16_bf16 v[64:79], v[128:131], v[152:155], v[64:79]
	ds_read_b128 v[220:223], v187 offset:6688
	v_add_f32_e32 v82, v98, v82
	v_add_f32_e32 v242, v242, v82
	v_add_f32_e32 v83, v99, v83
	v_add_f32_e32 v243, v243, v83
	s_waitcnt lgkmcnt(5)
	v_mfma_f32_32x32x16_bf16 v[64:79], v[132:135], v[156:159], v[64:79]
	ds_read_b128 v[128:131], v187 offset:6720
	v_add_f32_e32 v84, v100, v84
	v_add_f32_e32 v240, v240, v84
	v_add_f32_e32 v85, v101, v85
	v_add_f32_e32 v241, v241, v85
	s_waitcnt lgkmcnt(5)
	v_mfma_f32_32x32x16_bf16 v[64:79], v[136:139], v[160:163], v[64:79]
	ds_read_b128 v[132:135], v209 offset:58464
	v_add_f32_e32 v86, v102, v86
	v_add_f32_e32 v238, v238, v86
	v_add_f32_e32 v87, v103, v87
	v_add_f32_e32 v239, v239, v87
	s_waitcnt lgkmcnt(5)
	v_mfma_f32_32x32x16_bf16 v[16:31], v[140:143], v[120:123], v[16:31]
	ds_read_b128 v[136:139], v209 offset:63072
	v_add_f32_e32 v88, v104, v88
	v_add_f32_e32 v236, v236, v88
	v_add_f32_e32 v89, v105, v89
	v_add_f32_e32 v237, v237, v89
	s_waitcnt lgkmcnt(5)
	v_mfma_f32_32x32x16_bf16 v[32:47], v[188:191], v[120:123], v[32:47]
	ds_read_b128 v[140:143], v187 offset:6752
	v_add_f32_e32 v90, v106, v90
	v_add_f32_e32 v234, v234, v90
	v_add_f32_e32 v91, v107, v91
	v_add_f32_e32 v235, v235, v91
	s_waitcnt lgkmcnt(5)
	v_mfma_f32_32x32x16_bf16 v[48:63], v[168:171], v[164:167], v[0:15]
	ds_read_b128 v[188:191], v187 offset:6784
	v_exp_f32_e32 v64, v64
	v_exp_f32_e32 v65, v65
	v_exp_f32_e32 v66, v66
	v_exp_f32_e32 v67, v67
	s_waitcnt lgkmcnt(5)
	v_mfma_f32_32x32x16_bf16 v[48:63], v[220:223], v[144:147], v[48:63]
	ds_read_b128 v[168:171], v187 offset:6816
	v_exp_f32_e32 v68, v68
	v_exp_f32_e32 v69, v69
	v_exp_f32_e32 v70, v70
	v_exp_f32_e32 v71, v71
	s_waitcnt lgkmcnt(5)
	v_mfma_f32_32x32x16_bf16 v[48:63], v[128:131], v[148:151], v[48:63]
	ds_read_b128 v[128:131], v209 offset:13312
	v_cvt_pk_bf16_f32 v112, v64, v65
	v_cvt_pk_bf16_f32 v113, v66, v67
	v_cvt_pk_bf16_f32 v114, v68, v69
	v_cvt_pk_bf16_f32 v115, v70, v71
	s_waitcnt lgkmcnt(5)
	v_mfma_f32_32x32x16_bf16 v[16:31], v[132:135], v[124:127], v[16:31]
	ds_read_b128 v[132:135], v209 offset:17920
	v_exp_f32_e32 v72, v72
	v_exp_f32_e32 v73, v73
	v_exp_f32_e32 v74, v74
	v_exp_f32_e32 v75, v75
	s_waitcnt lgkmcnt(5)
	v_mfma_f32_32x32x16_bf16 v[32:47], v[136:139], v[124:127], v[32:47]
	ds_read_b128 v[136:139], v209 offset:13344
	v_exp_f32_e32 v76, v76
	v_exp_f32_e32 v77, v77
	v_exp_f32_e32 v78, v78
	v_exp_f32_e32 v79, v79
	s_waitcnt lgkmcnt(5)
	v_mfma_f32_32x32x16_bf16 v[48:63], v[140:143], v[152:155], v[48:63]
	ds_read_b128 v[140:143], v209 offset:17952
	v_cvt_pk_bf16_f32 v116, v72, v73
	v_cvt_pk_bf16_f32 v117, v74, v75
	v_cvt_pk_bf16_f32 v118, v76, v77
	v_cvt_pk_bf16_f32 v119, v78, v79
	s_waitcnt lgkmcnt(5)
	v_mfma_f32_32x32x16_bf16 v[48:63], v[188:191], v[156:159], v[48:63]
	v_add_f32_e32 v92, v108, v92
	v_add_f32_e32 v232, v232, v92
	v_add_f32_e32 v93, v109, v93
	v_add_f32_e32 v233, v233, v93
	s_waitcnt lgkmcnt(4)
	v_mfma_f32_32x32x16_bf16 v[48:63], v[168:171], v[160:163], v[48:63]
	v_add_f32_e32 v94, v110, v94
	v_add_f32_e32 v230, v230, v94
	v_add_f32_e32 v95, v111, v95
	v_add_f32_e32 v231, v231, v95
	s_waitcnt lgkmcnt(4)
	s_barrier
	s_add_i32 s14, s14, 1
	s_cmp_lt_u32 s14, 21
	s_cbranch_scc1 .Lattn_fx_loop
; template <bool FIXED> __device__ __forceinline__ void attn_unit(unsigned char* ws, LAS unsigned char* lds, int b, int h, int qb, const int tid, const float sbound) {
;     ...
;     if constexpr (FIXED) { for (int kt = 0; kt < SEQ / 64; kt += 2) { ATT_STEP_FIXED(pA0, pA1, pB0, pB1, kt); ATT_STEP_FIXED(pB0, pB1, pA0, pA1, kt + 1); }
	ds_read_b128 v[188:191], v187 offset:22528
	ds_read_b128 v[168:171], v187 offset:22560
	s_waitcnt lgkmcnt(5)
	v_mfma_f32_32x32x16_bf16 v[16:31], v[128:131], v[112:115], v[16:31]
	ds_read_b128 v[220:223], v187 offset:22592
	s_nop 3
	v_exp_f32_e32 v48, v48
	v_exp_f32_e32 v49, v49
	v_exp_f32_e32 v50, v50
	v_exp_f32_e32 v51, v51
	s_waitcnt lgkmcnt(5)
	v_mfma_f32_32x32x16_bf16 v[32:47], v[132:135], v[112:115], v[32:47]
	ds_read_b128 v[128:131], v187 offset:22624
	v_exp_f32_e32 v52, v52
	v_exp_f32_e32 v53, v53
	v_exp_f32_e32 v54, v54
	v_exp_f32_e32 v55, v55
	s_waitcnt lgkmcnt(5)
	v_mfma_f32_32x32x16_bf16 v[16:31], v[136:139], v[116:119], v[16:31]
	ds_read_b128 v[132:135], v187 offset:22656
	v_cvt_pk_bf16_f32 v120, v48, v49
	v_cvt_pk_bf16_f32 v121, v50, v51
	v_cvt_pk_bf16_f32 v122, v52, v53
	v_cvt_pk_bf16_f32 v123, v54, v55
	s_waitcnt lgkmcnt(5)
	v_mfma_f32_32x32x16_bf16 v[32:47], v[140:143], v[116:119], v[32:47]
	ds_read_b128 v[136:139], v187 offset:22688
	v_exp_f32_e32 v56, v56
	v_exp_f32_e32 v57, v57
	v_exp_f32_e32 v58, v58
	v_exp_f32_e32 v59, v59
	s_waitcnt lgkmcnt(5)
	v_mfma_f32_32x32x16_bf16 v[96:111], v[188:191], v[164:167], v[0:15]
	ds_read_b128 v[140:143], v209 offset:13376
	v_exp_f32_e32 v60, v60
	v_exp_f32_e32 v61, v61
	v_exp_f32_e32 v62, v62
	v_exp_f32_e32 v63, v63
	s_waitcnt lgkmcnt(5)
	v_mfma_f32_32x32x16_bf16 v[96:111], v[168:171], v[144:147], v[96:111]
	ds_read_b128 v[188:191], v209 offset:17984
	v_cvt_pk_bf16_f32 v124, v56, v57
	v_cvt_pk_bf16_f32 v125, v58, v59
	v_cvt_pk_bf16_f32 v126, v60, v61
	v_cvt_pk_bf16_f32 v127, v62, v63
	s_waitcnt lgkmcnt(5)
	v_mfma_f32_32x32x16_bf16 v[96:111], v[220:223], v[148:151], v[96:111]
	ds_read_b128 v[168:171], v187 offset:29184
	v_add_f32_e32 v48, v64, v48
	v_add_f32_e32 v244, v244, v48
	v_add_f32_e32 v49, v65, v49
	v_add_f32_e32 v245, v245, v49
	s_waitcnt lgkmcnt(5)
	v_mfma_f32_32x32x16_bf16 v[96:111], v[128:131], v[152:155], v[96:111]
	ds_read_b128 v[220:223], v187 offset:29216
	v_add_f32_e32 v50, v66, v50
	v_add_f32_e32 v242, v242, v50
	v_add_f32_e32 v51, v67, v51
	v_add_f32_e32 v243, v243, v51
	s_waitcnt lgkmcnt(5)
	v_mfma_f32_32x32x16_bf16 v[96:111], v[132:135], v[156:159], v[96:111]
	ds_read_b128 v[128:131], v187 offset:29248
	v_add_f32_e32 v52, v68, v52
	v_add_f32_e32 v240, v240, v52
	v_add_f32_e32 v53, v69, v53
	v_add_f32_e32 v241, v241, v53
	s_waitcnt lgkmcnt(5)
	v_mfma_f32_32x32x16_bf16 v[96:111], v[136:139], v[160:163], v[96:111]
	ds_read_b128 v[132:135], v209 offset:13408
	v_add_f32_e32 v54, v70, v54
	v_add_f32_e32 v238, v238, v54
	v_add_f32_e32 v55, v71, v55
	v_add_f32_e32 v239, v239, v55
	s_waitcnt lgkmcnt(5)
	v_mfma_f32_32x32x16_bf16 v[16:31], v[140:143], v[120:123], v[16:31]
	ds_read_b128 v[136:139], v209 offset:18016
	v_add_f32_e32 v56, v72, v56
	v_add_f32_e32 v236, v236, v56
	v_add_f32_e32 v57, v73, v57
	v_add_f32_e32 v237, v237, v57
	s_waitcnt lgkmcnt(5)
	v_mfma_f32_32x32x16_bf16 v[32:47], v[188:191], v[120:123], v[32:47]
	ds_read_b128 v[140:143], v187 offset:29280
	v_add_f32_e32 v58, v74, v58
	v_add_f32_e32 v234, v234, v58
	v_add_f32_e32 v59, v75, v59
	v_add_f32_e32 v235, v235, v59
	s_waitcnt lgkmcnt(5)
	v_mfma_f32_32x32x16_bf16 v[80:95], v[168:171], v[164:167], v[0:15]
	ds_read_b128 v[188:191], v187 offset:29312
	v_exp_f32_e32 v96, v96
	v_exp_f32_e32 v97, v97
	v_exp_f32_e32 v98, v98
	v_exp_f32_e32 v99, v99
	s_waitcnt lgkmcnt(5)
	v_mfma_f32_32x32x16_bf16 v[80:95], v[220:223], v[144:147], v[80:95]
	ds_read_b128 v[168:171], v187 offset:29344
	v_exp_f32_e32 v100, v100
	v_exp_f32_e32 v101, v101
	v_exp_f32_e32 v102, v102
	v_exp_f32_e32 v103, v103
	s_waitcnt lgkmcnt(5)
	v_mfma_f32_32x32x16_bf16 v[80:95], v[128:131], v[148:151], v[80:95]
	ds_read_b128 v[128:131], v209 offset:35840
	v_cvt_pk_bf16_f32 v112, v96, v97
	v_cvt_pk_bf16_f32 v113, v98, v99
	v_cvt_pk_bf16_f32 v114, v100, v101
	v_cvt_pk_bf16_f32 v115, v102, v103
	s_waitcnt lgkmcnt(5)
	v_mfma_f32_32x32x16_bf16 v[16:31], v[132:135], v[124:127], v[16:31]
	ds_read_b128 v[132:135], v209 offset:40448
	v_exp_f32_e32 v104, v104
	v_exp_f32_e32 v105, v105
	v_exp_f32_e32 v106, v106
	v_exp_f32_e32 v107, v107
	s_waitcnt lgkmcnt(5)
	v_mfma_f32_32x32x16_bf16 v[32:47], v[136:139], v[124:127], v[32:47]
	ds_read_b128 v[136:139], v209 offset:35872
	v_exp_f32_e32 v108, v108
	v_exp_f32_e32 v109, v109
	v_exp_f32_e32 v110, v110
	v_exp_f32_e32 v111, v111
	s_waitcnt lgkmcnt(5)
	v_mfma_f32_32x32x16_bf16 v[80:95], v[140:143], v[152:155], v[80:95]
	ds_read_b128 v[140:143], v209 offset:40480
	v_cvt_pk_bf16_f32 v116, v104, v105
	v_cvt_pk_bf16_f32 v117, v106, v107
	v_cvt_pk_bf16_f32 v118, v108, v109
	v_cvt_pk_bf16_f32 v119, v110, v111
	s_waitcnt lgkmcnt(5)
	v_mfma_f32_32x32x16_bf16 v[80:95], v[188:191], v[156:159], v[80:95]
	v_add_f32_e32 v60, v76, v60
	v_add_f32_e32 v232, v232, v60
	v_add_f32_e32 v61, v77, v61
	v_add_f32_e32 v233, v233, v61
	s_waitcnt lgkmcnt(4)
	v_mfma_f32_32x32x16_bf16 v[80:95], v[168:171], v[160:163], v[80:95]
	v_add_f32_e32 v62, v78, v62
	v_add_f32_e32 v230, v230, v62
	v_add_f32_e32 v63, v79, v63
	v_add_f32_e32 v231, v231, v63
	s_waitcnt lgkmcnt(4)
	s_barrier
; template <bool FIXED> __device__ __forceinline__ void attn_unit(unsigned char* ws, LAS unsigned char* lds, int b, int h, int qb, const int tid, const float sbound) {
;     ...
;     if constexpr (FIXED) { for (int kt = 0; kt < SEQ / 64; kt += 2) { ATT_STEP_FIXED(pA0, pA1, pB0, pB1, kt); ATT_STEP_FIXED(pB0, pB1, pA0, pA1, kt + 1); }
; #pragma unroll
;         for (int r = 0; r < 16; ++r) lsum += lacc[r]; }
	ds_read_b128 v[188:191], v209 offset:35904
	ds_read_b128 v[168:171], v209 offset:40512
	s_waitcnt lgkmcnt(5)
	v_mfma_f32_32x32x16_bf16 v[16:31], v[128:131], v[112:115], v[16:31]
	ds_read_b128 v[220:223], v209 offset:35936
	s_nop 3
	v_exp_f32_e32 v80, v80
	v_exp_f32_e32 v81, v81
	v_exp_f32_e32 v82, v82
	v_exp_f32_e32 v83, v83
	v_exp_f32_e32 v84, v84
	v_exp_f32_e32 v85, v85
	v_exp_f32_e32 v86, v86
	v_exp_f32_e32 v87, v87
	s_waitcnt lgkmcnt(5)
	v_mfma_f32_32x32x16_bf16 v[32:47], v[132:135], v[112:115], v[32:47]
	ds_read_b128 v[128:131], v209 offset:40544
	v_cvt_pk_bf16_f32 v120, v80, v81
	v_cvt_pk_bf16_f32 v121, v82, v83
	v_cvt_pk_bf16_f32 v122, v84, v85
	v_cvt_pk_bf16_f32 v123, v86, v87
	v_exp_f32_e32 v88, v88
	v_exp_f32_e32 v89, v89
	v_exp_f32_e32 v90, v90
	v_exp_f32_e32 v91, v91
	s_waitcnt lgkmcnt(5)
	v_mfma_f32_32x32x16_bf16 v[16:31], v[136:139], v[116:119], v[16:31]
	v_exp_f32_e32 v92, v92
	v_exp_f32_e32 v93, v93
	v_exp_f32_e32 v94, v94
	v_exp_f32_e32 v95, v95
	s_waitcnt lgkmcnt(4)
	v_mfma_f32_32x32x16_bf16 v[32:47], v[140:143], v[116:119], v[32:47]
	v_cvt_pk_bf16_f32 v124, v88, v89
	v_cvt_pk_bf16_f32 v125, v90, v91
	v_cvt_pk_bf16_f32 v126, v92, v93
	v_cvt_pk_bf16_f32 v127, v94, v95
	s_waitcnt lgkmcnt(3)
	v_mfma_f32_32x32x16_bf16 v[16:31], v[188:191], v[120:123], v[16:31]
	v_add_f32_e32 v80, v96, v80
	v_add_f32_e32 v244, v244, v80
	v_add_f32_e32 v81, v97, v81
	v_add_f32_e32 v245, v245, v81
	v_add_f32_e32 v82, v98, v82
	v_add_f32_e32 v242, v242, v82
	v_add_f32_e32 v83, v99, v83
	v_add_f32_e32 v243, v243, v83
	s_waitcnt lgkmcnt(2)
	v_mfma_f32_32x32x16_bf16 v[32:47], v[168:171], v[120:123], v[32:47]
	v_add_f32_e32 v84, v100, v84
	v_add_f32_e32 v240, v240, v84
	v_add_f32_e32 v85, v101, v85
	v_add_f32_e32 v241, v241, v85
	v_add_f32_e32 v86, v102, v86
	v_add_f32_e32 v238, v238, v86
	v_add_f32_e32 v87, v103, v87
	v_add_f32_e32 v239, v239, v87
	s_waitcnt lgkmcnt(1)
	v_mfma_f32_32x32x16_bf16 v[16:31], v[220:223], v[124:127], v[16:31]
	v_add_f32_e32 v88, v104, v88
	v_add_f32_e32 v236, v236, v88
	v_add_f32_e32 v89, v105, v89
	v_add_f32_e32 v237, v237, v89
	v_add_f32_e32 v90, v106, v90
	v_add_f32_e32 v234, v234, v90
	v_add_f32_e32 v91, v107, v91
	v_add_f32_e32 v235, v235, v91
	s_waitcnt lgkmcnt(0)
	v_mfma_f32_32x32x16_bf16 v[32:47], v[128:131], v[124:127], v[32:47]
	v_add_f32_e32 v92, v108, v92
	v_add_f32_e32 v232, v232, v92
	v_add_f32_e32 v93, v109, v93
	v_add_f32_e32 v233, v233, v93
	v_add_f32_e32 v94, v110, v94
	v_add_f32_e32 v230, v230, v94
	v_add_f32_e32 v95, v111, v95
	v_add_f32_e32 v231, v231, v95
	s_waitcnt lgkmcnt(0)
	s_barrier
